# v18 + GLA chunk k_dec stage: the 16 k rows fetched together instead of 8 serialised load pairs
# speedup vs baseline: 1.0052x; 1.0052x over previous
.LBB0_389:
	v_mov_b32_e32 v0, v1
	s_ashr_i32 s66, s21, 2
	v_mbcnt_lo_u32_b32 v0, -1, v0
	v_mbcnt_hi_u32_b32 v0, -1, v0
	v_add_u32_e32 v10, s54, v0
	s_ashr_i32 s67, s66, 31
	v_ashrrev_i32_e32 v6, 5, v10
	s_lshl_b64 s[6:7], s[66:67], 6
	v_ashrrev_i32_e32 v7, 31, v6
	v_lshl_add_u64 v[2:3], s[6:7], 0, v[6:7]
	s_and_b32 s0, s21, 3
	v_lshlrev_b64 v[2:3], 13, v[2:3]
	v_and_b32_e32 v16, 31, v10
	v_lshl_add_u64 v[2:3], s[18:19], 0, v[2:3]
	s_lshl_b32 s8, s0, 9
	s_mov_b32 s9, s87
	v_lshlrev_b32_e32 v0, 4, v16
	v_lshl_add_u64 v[2:3], v[2:3], 0, s[8:9]
	v_lshl_add_u64 v[2:3], v[2:3], 0, v[0:1]
	global_load_dwordx4 v[86:89], v[2:3], off offset:3712
	v_add_u32_e32 v8, 0, v0
	v_lshl_add_u32 v102, v6, 9, v8
	v_add_u32_e32 v9, 0x200, v10
	v_and_b32_e32 v11, 0x7f, v10
	s_lshl_b32 s86, s0, 8
	s_movk_i32 s0, 0x5000
	v_ashrrev_i32_e32 v17, 7, v10
	v_lshl_add_u32 v25, v17, 10, 0
	v_mov_b32_e32 v44, 0x41b17218
	v_ashrrev_i32_e32 v6, 5, v9
	v_ashrrev_i32_e32 v7, 31, v6
	v_lshl_add_u64 v[2:3], s[6:7], 0, v[6:7]
	v_lshlrev_b64 v[2:3], 13, v[2:3]
	v_lshl_add_u64 v[2:3], s[18:19], 0, v[2:3]
	v_lshl_add_u64 v[2:3], v[2:3], 0, s[8:9]
	v_lshl_add_u64 v[2:3], v[2:3], 0, v[0:1]
	global_load_dwordx4 v[90:93], v[2:3], off offset:3712
	v_lshl_add_u32 v103, v6, 9, v8
	v_add_u32_e32 v2, 0x400, v10
	v_ashrrev_i32_e32 v6, 5, v2
	v_ashrrev_i32_e32 v7, 31, v6
	v_lshl_add_u64 v[2:3], s[6:7], 0, v[6:7]
	v_lshlrev_b64 v[2:3], 13, v[2:3]
	v_lshl_add_u64 v[2:3], s[18:19], 0, v[2:3]
	v_lshl_add_u64 v[2:3], v[2:3], 0, s[8:9]
	v_lshl_add_u64 v[2:3], v[2:3], 0, v[0:1]
	global_load_dwordx4 v[94:97], v[2:3], off offset:3712
	v_lshl_add_u32 v104, v6, 9, v8
	v_add_u32_e32 v2, 0x600, v10
	v_ashrrev_i32_e32 v6, 5, v2
	v_ashrrev_i32_e32 v7, 31, v6
	v_lshl_add_u64 v[2:3], s[6:7], 0, v[6:7]
	v_lshlrev_b64 v[2:3], 13, v[2:3]
	v_lshl_add_u64 v[2:3], s[18:19], 0, v[2:3]
	v_lshl_add_u64 v[2:3], v[2:3], 0, s[8:9]
	v_lshl_add_u64 v[2:3], v[2:3], 0, v[0:1]
	global_load_dwordx4 v[98:101], v[2:3], off offset:3712
	v_lshl_add_u32 v105, v6, 9, v8
	v_lshl_add_u32 v6, v10, 2, 0
	v_lshlrev_b32_e32 v7, 2, v11
	v_readfirstlane_b32 s9, v10
	v_ashrrev_i32_e32 v4, 4, v10
	v_and_b32_e32 v0, 15, v10
	v_ashrrev_i32_e32 v5, 31, v4
	v_lshlrev_b32_e32 v0, 1, v0
	v_lshl_add_u64 v[4:5], s[6:7], 0, v[4:5]
	v_lshl_add_u64 v[2:3], s[18:19], 0, v[0:1]
	v_lshlrev_b64 v[4:5], 13, v[4:5]
	v_lshl_add_u64 v[4:5], v[2:3], 0, v[4:5]
	v_add_co_u32_e32 v4, vcc, s91, v4
	s_nop 1
	v_addc_co_u32_e32 v5, vcc, 0, v5, vcc
	global_load_ushort v106, v[4:5], off offset:1664
	v_ashrrev_i32_e32 v4, 4, v9
	v_ashrrev_i32_e32 v5, 31, v4
	v_lshl_add_u64 v[4:5], s[6:7], 0, v[4:5]
	v_lshlrev_b64 v[4:5], 13, v[4:5]
	v_lshl_add_u64 v[2:3], v[2:3], 0, v[4:5]
	v_add_co_u32_e32 v2, vcc, s91, v2
	s_nop 1
	v_addc_co_u32_e32 v3, vcc, 0, v3, vcc
	global_load_ushort v107, v[2:3], off offset:1664
	s_waitcnt vmcnt(5)
	ds_write_b128 v102, v[86:89]
	s_waitcnt vmcnt(4)
	ds_write_b128 v103, v[90:93]
	s_waitcnt vmcnt(3)
	ds_write_b128 v104, v[94:97]
	s_waitcnt vmcnt(2)
	ds_write_b128 v105, v[98:101]
	s_waitcnt vmcnt(0)
	v_lshlrev_b32_e32 v106, 16, v106
	v_lshlrev_b32_e32 v107, 16, v107
	ds_write2st64_b32 v6, v106, v107 offset0:208 offset1:216
	v_or_b32_e32 v0, s8, v7
	v_lshl_add_u64 v[4:5], s[14:15], 0, v[0:1]
	v_add_co_u32_e32 v2, vcc, s91, v4
	s_waitcnt lgkmcnt(0)
	s_nop 0
	v_addc_co_u32_e32 v3, vcc, 0, v5, vcc
	v_add_co_u32_e32 v8, vcc, s37, v4
	s_barrier
	s_nop 0
	v_addc_co_u32_e32 v9, vcc, 0, v5, vcc
	global_load_dword v18, v0, s[14:15]
	global_load_dword v19, v0, s[14:15] offset:2048
	global_load_dword v20, v[8:9], off offset:-4096
	global_load_dword v21, v[2:3], off offset:2048
	global_load_dword v12, v[8:9], off
	global_load_dword v13, v[8:9], off offset:2048
	v_add_co_u32_e32 v2, vcc, s56, v4
	s_mov_b32 s8, 0xbfb8aa3b
	s_nop 0
	v_addc_co_u32_e32 v3, vcc, 0, v5, vcc
	v_add_co_u32_e32 v22, vcc, s79, v4
	s_nop 1
	v_addc_co_u32_e32 v23, vcc, 0, v5, vcc
	global_load_dword v14, v[22:23], off offset:-4096
	global_load_dword v15, v[2:3], off offset:2048
	global_load_dword v8, v[22:23], off
	global_load_dword v9, v[22:23], off offset:2048
	v_add_co_u32_e32 v2, vcc, s0, v4
	s_movk_i32 s0, 0x7000
	s_nop 0
	v_addc_co_u32_e32 v3, vcc, 0, v5, vcc
	v_add_co_u32_e32 v26, vcc, s57, v4
	s_nop 1
	v_addc_co_u32_e32 v27, vcc, 0, v5, vcc
	global_load_dword v23, v[26:27], off offset:-4096
	global_load_dword v24, v[2:3], off offset:2048
	s_nop 0
	global_load_dword v2, v[26:27], off
	global_load_dword v3, v[26:27], off offset:2048
	v_add_co_u32_e32 v26, vcc, s0, v4
	s_mov_b32 s0, 0x3d800000
	s_nop 0
	v_addc_co_u32_e32 v27, vcc, 0, v5, vcc
	global_load_dword v4, v[26:27], off
	global_load_dword v5, v[26:27], off offset:2048
	s_nop 0
	global_load_dword v0, v0, s[16:17]
	ds_read_b128 v[26:29], v25 offset:53248
	ds_read_b128 v[30:33], v25 offset:53264
	ds_read_b128 v[34:37], v25 offset:53280
	ds_read_b128 v[38:41], v25 offset:53296
	s_waitcnt vmcnt(0) lgkmcnt(3)
	v_fma_f32 v22, v18, v26, v0
	v_fmac_f32_e32 v22, v19, v27
	v_fmac_f32_e32 v22, v20, v28
	v_fmac_f32_e32 v22, v21, v29
	s_waitcnt lgkmcnt(2)
	v_fmac_f32_e32 v22, v12, v30
	v_fmac_f32_e32 v22, v13, v31
	v_fmac_f32_e32 v22, v14, v32
	v_fmac_f32_e32 v22, v15, v33
	s_waitcnt lgkmcnt(1)
	v_fmac_f32_e32 v22, v8, v34
	v_fmac_f32_e32 v22, v9, v35
	v_fmac_f32_e32 v22, v23, v36
	v_fmac_f32_e32 v22, v24, v37
	s_waitcnt lgkmcnt(0)
	v_pk_mul_f32 v[26:27], v[2:3], v[38:39]
	s_nop 0
	v_add_f32_e32 v22, v22, v26
	v_add_f32_e32 v22, v22, v27
	v_pk_mul_f32 v[26:27], v[4:5], v[40:41]
	s_nop 0
	v_add_f32_e32 v22, v22, v26
	v_add_f32_e32 v22, v22, v27
	v_min_f32_e32 v26, 0, v22
	v_mul_f32_e64 v22, |v22|, s8
	v_exp_f32_e32 v22, v22
	s_nop 0
	v_add_f32_e32 v22, 1.0, v22
	v_cmp_gt_f32_e32 vcc, s5, v22
	s_nop 1
	v_cndmask_b32_e64 v27, 0, 32, vcc
	v_ldexp_f32 v22, v22, v27
	v_log_f32_e32 v22, v22
	s_nop 0
	v_mul_f32_e32 v27, 0x3f317217, v22
	v_fma_f32 v27, v22, s51, -v27
	v_fmac_f32_e32 v27, 0x3377d1cf, v22
	v_fmac_f32_e32 v27, 0x3f317217, v22
	v_cmp_lt_f32_e64 s[12:13], |v22|, s53
	s_nop 1
	v_cndmask_b32_e64 v22, v22, v27, s[12:13]
	v_cndmask_b32_e32 v27, 0, v44, vcc
	v_sub_f32_e32 v22, v22, v27
	v_sub_f32_e32 v22, v26, v22
	ds_read_b128 v[26:29], v25 offset:53312
	v_fma_f32 v22, v22, s0, 0
	s_mov_b32 s0, 0x8000
	s_waitcnt lgkmcnt(0)
	v_fma_f32 v30, v18, v26, v0
	v_fmac_f32_e32 v30, v19, v27
	v_fmac_f32_e32 v30, v20, v28
	v_fmac_f32_e32 v30, v21, v29
	ds_read_b128 v[26:29], v25 offset:53328
	s_waitcnt lgkmcnt(0)
	v_fmac_f32_e32 v30, v12, v26
	v_fmac_f32_e32 v30, v13, v27
	v_fmac_f32_e32 v30, v14, v28
	v_fmac_f32_e32 v30, v15, v29
	ds_read_b128 v[26:29], v25 offset:53344
	s_waitcnt lgkmcnt(0)
	v_fmac_f32_e32 v30, v8, v26
	v_fmac_f32_e32 v30, v9, v27
	v_fmac_f32_e32 v30, v23, v28
	v_fmac_f32_e32 v30, v24, v29
	ds_read_b128 v[26:29], v25 offset:53360
	s_waitcnt lgkmcnt(0)
	v_pk_mul_f32 v[26:27], v[2:3], v[26:27]
	s_nop 0
	v_add_f32_e32 v26, v30, v26
	v_add_f32_e32 v30, v26, v27
	v_pk_mul_f32 v[26:27], v[4:5], v[28:29]
	s_nop 0
	v_add_f32_e32 v26, v30, v26
	v_add_f32_e32 v26, v26, v27
	v_min_f32_e32 v27, 0, v26
	v_mul_f32_e64 v26, |v26|, s8
	v_exp_f32_e32 v26, v26
	s_nop 0
	v_add_f32_e32 v26, 1.0, v26
	v_cmp_gt_f32_e32 vcc, s5, v26
	s_nop 1
	v_cndmask_b32_e64 v28, 0, 32, vcc
	v_ldexp_f32 v26, v26, v28
	v_log_f32_e32 v26, v26
	s_nop 0
	v_mul_f32_e32 v28, 0x3f317217, v26
	v_fma_f32 v28, v26, s51, -v28
	v_fmac_f32_e32 v28, 0x3377d1cf, v26
	v_fmac_f32_e32 v28, 0x3f317217, v26
	v_cmp_lt_f32_e64 s[12:13], |v26|, s53
	s_nop 1
	v_cndmask_b32_e64 v26, v26, v28, s[12:13]
	v_cndmask_b32_e32 v28, 0, v44, vcc
	v_sub_f32_e32 v26, v26, v28
	ds_read_b128 v[28:31], v25 offset:53376
	v_sub_f32_e32 v26, v27, v26
	v_fmamk_f32 v26, v26, 0x3d800000, v22
	s_waitcnt lgkmcnt(0)
	v_fma_f32 v27, v18, v28, v0
	v_fmac_f32_e32 v27, v19, v29
	v_fmac_f32_e32 v27, v20, v30
	v_fmac_f32_e32 v27, v21, v31
	ds_read_b128 v[28:31], v25 offset:53392
	s_waitcnt lgkmcnt(0)
	v_fmac_f32_e32 v27, v12, v28
	v_fmac_f32_e32 v27, v13, v29
	v_fmac_f32_e32 v27, v14, v30
	v_fmac_f32_e32 v27, v15, v31
	ds_read_b128 v[28:31], v25 offset:53408
	s_waitcnt lgkmcnt(0)
	v_fmac_f32_e32 v27, v8, v28
	v_fmac_f32_e32 v27, v9, v29
	v_fmac_f32_e32 v27, v23, v30
	v_fmac_f32_e32 v27, v24, v31
	ds_read_b128 v[28:31], v25 offset:53424
	s_waitcnt lgkmcnt(0)
	v_pk_mul_f32 v[28:29], v[2:3], v[28:29]
	s_nop 0
	v_add_f32_e32 v27, v27, v28
	v_add_f32_e32 v27, v27, v29
	v_pk_mul_f32 v[28:29], v[4:5], v[30:31]
	s_nop 0
	v_add_f32_e32 v27, v27, v28
	v_add_f32_e32 v27, v27, v29
	v_min_f32_e32 v28, 0, v27
	v_mul_f32_e64 v27, |v27|, s8
	v_exp_f32_e32 v27, v27
	s_nop 0
	v_add_f32_e32 v27, 1.0, v27
	v_cmp_gt_f32_e32 vcc, s5, v27
	s_nop 1
	v_cndmask_b32_e64 v29, 0, 32, vcc
	v_ldexp_f32 v27, v27, v29
	v_log_f32_e32 v27, v27
	s_nop 0
	v_mul_f32_e32 v29, 0x3f317217, v27
	v_fma_f32 v29, v27, s51, -v29
	v_fmac_f32_e32 v29, 0x3377d1cf, v27
	v_fmac_f32_e32 v29, 0x3f317217, v27
	v_cmp_lt_f32_e64 s[12:13], |v27|, s53
	s_nop 1
	v_cndmask_b32_e64 v27, v27, v29, s[12:13]
	v_cndmask_b32_e32 v29, 0, v44, vcc
	v_sub_f32_e32 v27, v27, v29
	v_sub_f32_e32 v27, v28, v27
	ds_read_b128 v[28:31], v25 offset:53440
	v_fmamk_f32 v27, v27, 0x3d800000, v26
	s_waitcnt lgkmcnt(0)
	v_fma_f32 v32, v18, v28, v0
	v_fmac_f32_e32 v32, v19, v29
	v_fmac_f32_e32 v32, v20, v30
	v_fmac_f32_e32 v32, v21, v31
	ds_read_b128 v[28:31], v25 offset:53456
	s_waitcnt lgkmcnt(0)
	v_fmac_f32_e32 v32, v12, v28
	v_fmac_f32_e32 v32, v13, v29
	v_fmac_f32_e32 v32, v14, v30
	v_fmac_f32_e32 v32, v15, v31
	ds_read_b128 v[28:31], v25 offset:53472
	s_waitcnt lgkmcnt(0)
	v_fmac_f32_e32 v32, v8, v28
	v_fmac_f32_e32 v32, v9, v29
	v_fmac_f32_e32 v32, v23, v30
	v_fmac_f32_e32 v32, v24, v31
	ds_read_b128 v[28:31], v25 offset:53488
	s_waitcnt lgkmcnt(0)
	v_pk_mul_f32 v[28:29], v[2:3], v[28:29]
	s_nop 0
	v_add_f32_e32 v28, v32, v28
	v_add_f32_e32 v32, v28, v29
	v_pk_mul_f32 v[28:29], v[4:5], v[30:31]
	s_nop 0
	v_add_f32_e32 v28, v32, v28
	v_add_f32_e32 v28, v28, v29
	v_min_f32_e32 v29, 0, v28
	v_mul_f32_e64 v28, |v28|, s8
	v_exp_f32_e32 v28, v28
	s_nop 0
	v_add_f32_e32 v28, 1.0, v28
	v_cmp_gt_f32_e32 vcc, s5, v28
	s_nop 1
	v_cndmask_b32_e64 v30, 0, 32, vcc
	v_ldexp_f32 v28, v28, v30
	v_log_f32_e32 v28, v28
	s_nop 0
	v_mul_f32_e32 v30, 0x3f317217, v28
	v_fma_f32 v30, v28, s51, -v30
	v_fmac_f32_e32 v30, 0x3377d1cf, v28
	v_fmac_f32_e32 v30, 0x3f317217, v28
	v_cmp_lt_f32_e64 s[12:13], |v28|, s53
	s_nop 1
	v_cndmask_b32_e64 v28, v28, v30, s[12:13]
	v_cndmask_b32_e32 v30, 0, v44, vcc
	v_sub_f32_e32 v28, v28, v30
	ds_read_b128 v[30:33], v25 offset:53504
	v_sub_f32_e32 v28, v29, v28
	v_fmamk_f32 v28, v28, 0x3d800000, v27
	s_waitcnt lgkmcnt(0)
	v_fma_f32 v29, v18, v30, v0
	v_fmac_f32_e32 v29, v19, v31
	v_fmac_f32_e32 v29, v20, v32
	v_fmac_f32_e32 v29, v21, v33
	ds_read_b128 v[30:33], v25 offset:53520
	s_waitcnt lgkmcnt(0)
	v_fmac_f32_e32 v29, v12, v30
	v_fmac_f32_e32 v29, v13, v31
	v_fmac_f32_e32 v29, v14, v32
	v_fmac_f32_e32 v29, v15, v33
	ds_read_b128 v[30:33], v25 offset:53536
	s_waitcnt lgkmcnt(0)
	v_fmac_f32_e32 v29, v8, v30
	v_fmac_f32_e32 v29, v9, v31
	v_fmac_f32_e32 v29, v23, v32
	v_fmac_f32_e32 v29, v24, v33
	ds_read_b128 v[30:33], v25 offset:53552
	s_waitcnt lgkmcnt(0)
	v_pk_mul_f32 v[30:31], v[2:3], v[30:31]
	s_nop 0
	v_add_f32_e32 v29, v29, v30
	v_add_f32_e32 v29, v29, v31
	v_pk_mul_f32 v[30:31], v[4:5], v[32:33]
	s_nop 0
	v_add_f32_e32 v29, v29, v30
	v_add_f32_e32 v29, v29, v31
	v_min_f32_e32 v30, 0, v29
	v_mul_f32_e64 v29, |v29|, s8
	v_exp_f32_e32 v29, v29
	s_nop 0
	v_add_f32_e32 v29, 1.0, v29
	v_cmp_gt_f32_e32 vcc, s5, v29
	s_nop 1
	v_cndmask_b32_e64 v31, 0, 32, vcc
	v_ldexp_f32 v29, v29, v31
	v_log_f32_e32 v29, v29
	s_nop 0
	v_mul_f32_e32 v31, 0x3f317217, v29
	v_fma_f32 v31, v29, s51, -v31
	v_fmac_f32_e32 v31, 0x3377d1cf, v29
	v_fmac_f32_e32 v31, 0x3f317217, v29
	v_cmp_lt_f32_e64 s[12:13], |v29|, s53
	s_nop 1
	v_cndmask_b32_e64 v29, v29, v31, s[12:13]
	v_cndmask_b32_e32 v31, 0, v44, vcc
	v_sub_f32_e32 v29, v29, v31
	v_sub_f32_e32 v29, v30, v29
	ds_read_b128 v[30:33], v25 offset:53568
	v_fmamk_f32 v29, v29, 0x3d800000, v28
	s_waitcnt lgkmcnt(0)
	v_fma_f32 v34, v18, v30, v0
	v_fmac_f32_e32 v34, v19, v31
	v_fmac_f32_e32 v34, v20, v32
	v_fmac_f32_e32 v34, v21, v33
	ds_read_b128 v[30:33], v25 offset:53584
	s_waitcnt lgkmcnt(0)
	v_fmac_f32_e32 v34, v12, v30
	v_fmac_f32_e32 v34, v13, v31
	v_fmac_f32_e32 v34, v14, v32
	v_fmac_f32_e32 v34, v15, v33
	ds_read_b128 v[30:33], v25 offset:53600
	s_waitcnt lgkmcnt(0)
	v_fmac_f32_e32 v34, v8, v30
	v_fmac_f32_e32 v34, v9, v31
	v_fmac_f32_e32 v34, v23, v32
	v_fmac_f32_e32 v34, v24, v33
	ds_read_b128 v[30:33], v25 offset:53616
	s_waitcnt lgkmcnt(0)
	v_pk_mul_f32 v[30:31], v[2:3], v[30:31]
	s_nop 0
	v_add_f32_e32 v30, v34, v30
	v_add_f32_e32 v34, v30, v31
	v_pk_mul_f32 v[30:31], v[4:5], v[32:33]
	s_nop 0
	v_add_f32_e32 v30, v34, v30
	v_add_f32_e32 v30, v30, v31
	v_min_f32_e32 v31, 0, v30
	v_mul_f32_e64 v30, |v30|, s8
	v_exp_f32_e32 v30, v30
	s_nop 0
	v_add_f32_e32 v30, 1.0, v30
	v_cmp_gt_f32_e32 vcc, s5, v30
	s_nop 1
	v_cndmask_b32_e64 v32, 0, 32, vcc
	v_ldexp_f32 v30, v30, v32
	v_log_f32_e32 v30, v30
	s_nop 0
	v_mul_f32_e32 v32, 0x3f317217, v30
	v_fma_f32 v32, v30, s51, -v32
	v_fmac_f32_e32 v32, 0x3377d1cf, v30
	v_fmac_f32_e32 v32, 0x3f317217, v30
	v_cmp_lt_f32_e64 s[12:13], |v30|, s53
	s_nop 1
	v_cndmask_b32_e64 v30, v30, v32, s[12:13]
	v_cndmask_b32_e32 v32, 0, v44, vcc
	v_sub_f32_e32 v30, v30, v32
	ds_read_b128 v[32:35], v25 offset:53632
	v_sub_f32_e32 v30, v31, v30
	v_fmamk_f32 v30, v30, 0x3d800000, v29
	s_waitcnt lgkmcnt(0)
	v_fma_f32 v31, v18, v32, v0
	v_fmac_f32_e32 v31, v19, v33
	v_fmac_f32_e32 v31, v20, v34
	v_fmac_f32_e32 v31, v21, v35
	ds_read_b128 v[32:35], v25 offset:53648
	s_waitcnt lgkmcnt(0)
	v_fmac_f32_e32 v31, v12, v32
	v_fmac_f32_e32 v31, v13, v33
	v_fmac_f32_e32 v31, v14, v34
	v_fmac_f32_e32 v31, v15, v35
	ds_read_b128 v[32:35], v25 offset:53664
	s_waitcnt lgkmcnt(0)
	v_fmac_f32_e32 v31, v8, v32
	v_fmac_f32_e32 v31, v9, v33
	v_fmac_f32_e32 v31, v23, v34
	v_fmac_f32_e32 v31, v24, v35
	ds_read_b128 v[32:35], v25 offset:53680
	s_waitcnt lgkmcnt(0)
	v_pk_mul_f32 v[32:33], v[2:3], v[32:33]
	s_nop 0
	v_add_f32_e32 v31, v31, v32
	v_add_f32_e32 v31, v31, v33
	v_pk_mul_f32 v[32:33], v[4:5], v[34:35]
	s_nop 0
	v_add_f32_e32 v31, v31, v32
	v_add_f32_e32 v31, v31, v33
	v_min_f32_e32 v32, 0, v31
	v_mul_f32_e64 v31, |v31|, s8
	v_exp_f32_e32 v31, v31
	s_nop 0
	v_add_f32_e32 v31, 1.0, v31
	v_cmp_gt_f32_e32 vcc, s5, v31
	s_nop 1
	v_cndmask_b32_e64 v33, 0, 32, vcc
	v_ldexp_f32 v31, v31, v33
	v_log_f32_e32 v31, v31
	s_nop 0
	v_mul_f32_e32 v33, 0x3f317217, v31
	v_fma_f32 v33, v31, s51, -v33
	v_fmac_f32_e32 v33, 0x3377d1cf, v31
	v_fmac_f32_e32 v33, 0x3f317217, v31
	v_cmp_lt_f32_e64 s[12:13], |v31|, s53
	s_nop 1
	v_cndmask_b32_e64 v31, v31, v33, s[12:13]
	v_cndmask_b32_e32 v33, 0, v44, vcc
	v_sub_f32_e32 v31, v31, v33
	v_sub_f32_e32 v31, v32, v31
	ds_read_b128 v[32:35], v25 offset:53696
	v_fmamk_f32 v31, v31, 0x3d800000, v30
	s_waitcnt lgkmcnt(0)
	v_fma_f32 v36, v18, v32, v0
	v_fmac_f32_e32 v36, v19, v33
	v_fmac_f32_e32 v36, v20, v34
	v_fmac_f32_e32 v36, v21, v35
	ds_read_b128 v[32:35], v25 offset:53712
	s_waitcnt lgkmcnt(0)
	v_fmac_f32_e32 v36, v12, v32
	v_fmac_f32_e32 v36, v13, v33
	v_fmac_f32_e32 v36, v14, v34
	v_fmac_f32_e32 v36, v15, v35
	ds_read_b128 v[32:35], v25 offset:53728
	s_waitcnt lgkmcnt(0)
	v_fmac_f32_e32 v36, v8, v32
	v_fmac_f32_e32 v36, v9, v33
	v_fmac_f32_e32 v36, v23, v34
	v_fmac_f32_e32 v36, v24, v35
	ds_read_b128 v[32:35], v25 offset:53744
	s_waitcnt lgkmcnt(0)
	v_pk_mul_f32 v[32:33], v[2:3], v[32:33]
	s_nop 0
	v_add_f32_e32 v32, v36, v32
	v_add_f32_e32 v36, v32, v33
	v_pk_mul_f32 v[32:33], v[4:5], v[34:35]
	s_nop 0
	v_add_f32_e32 v32, v36, v32
	v_add_f32_e32 v32, v32, v33
	v_min_f32_e32 v33, 0, v32
	v_mul_f32_e64 v32, |v32|, s8
	v_exp_f32_e32 v32, v32
	s_nop 0
	v_add_f32_e32 v32, 1.0, v32
	v_cmp_gt_f32_e32 vcc, s5, v32
	s_nop 1
	v_cndmask_b32_e64 v34, 0, 32, vcc
	v_ldexp_f32 v32, v32, v34
	v_log_f32_e32 v32, v32
	s_nop 0
	v_mul_f32_e32 v34, 0x3f317217, v32
	v_fma_f32 v34, v32, s51, -v34
	v_fmac_f32_e32 v34, 0x3377d1cf, v32
	v_fmac_f32_e32 v34, 0x3f317217, v32
	v_cmp_lt_f32_e64 s[12:13], |v32|, s53
	s_nop 1
	v_cndmask_b32_e64 v32, v32, v34, s[12:13]
	v_cndmask_b32_e32 v34, 0, v44, vcc
	v_sub_f32_e32 v32, v32, v34
	ds_read_b128 v[34:37], v25 offset:53760
	v_sub_f32_e32 v32, v33, v32
	v_fmamk_f32 v32, v32, 0x3d800000, v31
	s_waitcnt lgkmcnt(0)
	v_fma_f32 v33, v18, v34, v0
	v_fmac_f32_e32 v33, v19, v35
	v_fmac_f32_e32 v33, v20, v36
	v_fmac_f32_e32 v33, v21, v37
	ds_read_b128 v[34:37], v25 offset:53776
	s_waitcnt lgkmcnt(0)
	v_fmac_f32_e32 v33, v12, v34
	v_fmac_f32_e32 v33, v13, v35
	v_fmac_f32_e32 v33, v14, v36
	v_fmac_f32_e32 v33, v15, v37
	ds_read_b128 v[34:37], v25 offset:53792
	s_waitcnt lgkmcnt(0)
	v_fmac_f32_e32 v33, v8, v34
	v_fmac_f32_e32 v33, v9, v35
	v_fmac_f32_e32 v33, v23, v36
	v_fmac_f32_e32 v33, v24, v37
	ds_read_b128 v[34:37], v25 offset:53808
	s_waitcnt lgkmcnt(0)
	v_pk_mul_f32 v[34:35], v[2:3], v[34:35]
	s_nop 0
	v_add_f32_e32 v33, v33, v34
	v_add_f32_e32 v33, v33, v35
	v_pk_mul_f32 v[34:35], v[4:5], v[36:37]
	s_nop 0
	v_add_f32_e32 v33, v33, v34
	v_add_f32_e32 v33, v33, v35
	v_min_f32_e32 v34, 0, v33
	v_mul_f32_e64 v33, |v33|, s8
	v_exp_f32_e32 v33, v33
	s_nop 0
	v_add_f32_e32 v33, 1.0, v33
	v_cmp_gt_f32_e32 vcc, s5, v33
	s_nop 1
	v_cndmask_b32_e64 v35, 0, 32, vcc
	v_ldexp_f32 v33, v33, v35
	v_log_f32_e32 v33, v33
	s_nop 0
	v_mul_f32_e32 v35, 0x3f317217, v33
	v_fma_f32 v35, v33, s51, -v35
	v_fmac_f32_e32 v35, 0x3377d1cf, v33
	v_fmac_f32_e32 v35, 0x3f317217, v33
	v_cmp_lt_f32_e64 s[12:13], |v33|, s53
	s_nop 1
	v_cndmask_b32_e64 v33, v33, v35, s[12:13]
	v_cndmask_b32_e32 v35, 0, v44, vcc
	v_sub_f32_e32 v33, v33, v35
	v_sub_f32_e32 v33, v34, v33
	ds_read_b128 v[34:37], v25 offset:53824
	v_fmamk_f32 v33, v33, 0x3d800000, v32
	s_waitcnt lgkmcnt(0)
	v_fma_f32 v38, v18, v34, v0
	v_fmac_f32_e32 v38, v19, v35
	v_fmac_f32_e32 v38, v20, v36
	v_fmac_f32_e32 v38, v21, v37
	ds_read_b128 v[34:37], v25 offset:53840
	s_waitcnt lgkmcnt(0)
	v_fmac_f32_e32 v38, v12, v34
	v_fmac_f32_e32 v38, v13, v35
	v_fmac_f32_e32 v38, v14, v36
	v_fmac_f32_e32 v38, v15, v37
	ds_read_b128 v[34:37], v25 offset:53856
	s_waitcnt lgkmcnt(0)
	v_fmac_f32_e32 v38, v8, v34
	v_fmac_f32_e32 v38, v9, v35
	v_fmac_f32_e32 v38, v23, v36
	v_fmac_f32_e32 v38, v24, v37
	ds_read_b128 v[34:37], v25 offset:53872
	s_waitcnt lgkmcnt(0)
	v_pk_mul_f32 v[34:35], v[2:3], v[34:35]
	s_nop 0
	v_add_f32_e32 v34, v38, v34
	v_add_f32_e32 v38, v34, v35
	v_pk_mul_f32 v[34:35], v[4:5], v[36:37]
	s_nop 0
	v_add_f32_e32 v34, v38, v34
	v_add_f32_e32 v34, v34, v35
	v_min_f32_e32 v35, 0, v34
	v_mul_f32_e64 v34, |v34|, s8
	v_exp_f32_e32 v34, v34
	s_nop 0
	v_add_f32_e32 v34, 1.0, v34
	v_cmp_gt_f32_e32 vcc, s5, v34
	s_nop 1
	v_cndmask_b32_e64 v36, 0, 32, vcc
	v_ldexp_f32 v34, v34, v36
	v_log_f32_e32 v34, v34
	s_nop 0
	v_mul_f32_e32 v36, 0x3f317217, v34
	v_fma_f32 v36, v34, s51, -v36
	v_fmac_f32_e32 v36, 0x3377d1cf, v34
	v_fmac_f32_e32 v36, 0x3f317217, v34
	v_cmp_lt_f32_e64 s[12:13], |v34|, s53
	s_nop 1
	v_cndmask_b32_e64 v34, v34, v36, s[12:13]
	v_cndmask_b32_e32 v36, 0, v44, vcc
	v_sub_f32_e32 v34, v34, v36
	ds_read_b128 v[36:39], v25 offset:53888
	v_sub_f32_e32 v34, v35, v34
	v_fmamk_f32 v34, v34, 0x3d800000, v33
	s_waitcnt lgkmcnt(0)
	v_fma_f32 v35, v18, v36, v0
	v_fmac_f32_e32 v35, v19, v37
	v_fmac_f32_e32 v35, v20, v38
	v_fmac_f32_e32 v35, v21, v39
	ds_read_b128 v[36:39], v25 offset:53904
	s_waitcnt lgkmcnt(0)
	v_fmac_f32_e32 v35, v12, v36
	v_fmac_f32_e32 v35, v13, v37
	v_fmac_f32_e32 v35, v14, v38
	v_fmac_f32_e32 v35, v15, v39
	ds_read_b128 v[36:39], v25 offset:53920
	s_waitcnt lgkmcnt(0)
	v_fmac_f32_e32 v35, v8, v36
	v_fmac_f32_e32 v35, v9, v37
	v_fmac_f32_e32 v35, v23, v38
	v_fmac_f32_e32 v35, v24, v39
	ds_read_b128 v[36:39], v25 offset:53936
	s_waitcnt lgkmcnt(0)
	v_pk_mul_f32 v[36:37], v[2:3], v[36:37]
	s_nop 0
	v_add_f32_e32 v35, v35, v36
	v_add_f32_e32 v35, v35, v37
	v_pk_mul_f32 v[36:37], v[4:5], v[38:39]
	s_nop 0
	v_add_f32_e32 v35, v35, v36
	v_add_f32_e32 v35, v35, v37
	v_min_f32_e32 v36, 0, v35
	v_mul_f32_e64 v35, |v35|, s8
	v_exp_f32_e32 v35, v35
	s_nop 0
	v_add_f32_e32 v35, 1.0, v35
	v_cmp_gt_f32_e32 vcc, s5, v35
	s_nop 1
	v_cndmask_b32_e64 v37, 0, 32, vcc
	v_ldexp_f32 v35, v35, v37
	v_log_f32_e32 v35, v35
	s_nop 0
	v_mul_f32_e32 v37, 0x3f317217, v35
	v_fma_f32 v37, v35, s51, -v37
	v_fmac_f32_e32 v37, 0x3377d1cf, v35
	v_fmac_f32_e32 v37, 0x3f317217, v35
	v_cmp_lt_f32_e64 s[12:13], |v35|, s53
	s_nop 1
	v_cndmask_b32_e64 v35, v35, v37, s[12:13]
	v_cndmask_b32_e32 v37, 0, v44, vcc
	v_sub_f32_e32 v35, v35, v37
	v_sub_f32_e32 v35, v36, v35
	ds_read_b128 v[36:39], v25 offset:53952
	v_fmamk_f32 v35, v35, 0x3d800000, v34
	s_waitcnt lgkmcnt(0)
	v_fma_f32 v40, v18, v36, v0
	v_fmac_f32_e32 v40, v19, v37
	v_fmac_f32_e32 v40, v20, v38
	v_fmac_f32_e32 v40, v21, v39
	ds_read_b128 v[36:39], v25 offset:53968
	s_waitcnt lgkmcnt(0)
	v_fmac_f32_e32 v40, v12, v36
	v_fmac_f32_e32 v40, v13, v37
	v_fmac_f32_e32 v40, v14, v38
	v_fmac_f32_e32 v40, v15, v39
	ds_read_b128 v[36:39], v25 offset:53984
	s_waitcnt lgkmcnt(0)
	v_fmac_f32_e32 v40, v8, v36
	v_fmac_f32_e32 v40, v9, v37
	v_fmac_f32_e32 v40, v23, v38
	v_fmac_f32_e32 v40, v24, v39
	ds_read_b128 v[36:39], v25 offset:54000
	s_waitcnt lgkmcnt(0)
	v_pk_mul_f32 v[36:37], v[2:3], v[36:37]
	s_nop 0
	v_add_f32_e32 v36, v40, v36
	v_add_f32_e32 v40, v36, v37
	v_pk_mul_f32 v[36:37], v[4:5], v[38:39]
	s_nop 0
	v_add_f32_e32 v36, v40, v36
	v_add_f32_e32 v36, v36, v37
	v_min_f32_e32 v37, 0, v36
	v_mul_f32_e64 v36, |v36|, s8
	v_exp_f32_e32 v36, v36
	s_nop 0
	v_add_f32_e32 v36, 1.0, v36
	v_cmp_gt_f32_e32 vcc, s5, v36
	s_nop 1
	v_cndmask_b32_e64 v38, 0, 32, vcc
	v_ldexp_f32 v36, v36, v38
	v_log_f32_e32 v36, v36
	s_nop 0
	v_mul_f32_e32 v38, 0x3f317217, v36
	v_fma_f32 v38, v36, s51, -v38
	v_fmac_f32_e32 v38, 0x3377d1cf, v36
	v_fmac_f32_e32 v38, 0x3f317217, v36
	v_cmp_lt_f32_e64 s[12:13], |v36|, s53
	s_nop 1
	v_cndmask_b32_e64 v36, v36, v38, s[12:13]
	v_cndmask_b32_e32 v38, 0, v44, vcc
	v_sub_f32_e32 v36, v36, v38
	ds_read_b128 v[38:41], v25 offset:54016
	v_sub_f32_e32 v36, v37, v36
	v_fmamk_f32 v36, v36, 0x3d800000, v35
	s_waitcnt lgkmcnt(0)
	v_fma_f32 v37, v18, v38, v0
	v_fmac_f32_e32 v37, v19, v39
	v_fmac_f32_e32 v37, v20, v40
	v_fmac_f32_e32 v37, v21, v41
	ds_read_b128 v[38:41], v25 offset:54032
	s_waitcnt lgkmcnt(0)
	v_fmac_f32_e32 v37, v12, v38
	v_fmac_f32_e32 v37, v13, v39
	v_fmac_f32_e32 v37, v14, v40
	v_fmac_f32_e32 v37, v15, v41
	ds_read_b128 v[38:41], v25 offset:54048
	s_waitcnt lgkmcnt(0)
	v_fmac_f32_e32 v37, v8, v38
	v_fmac_f32_e32 v37, v9, v39
	v_fmac_f32_e32 v37, v23, v40
	v_fmac_f32_e32 v37, v24, v41
	ds_read_b128 v[38:41], v25 offset:54064
	s_waitcnt lgkmcnt(0)
	v_pk_mul_f32 v[38:39], v[2:3], v[38:39]
	s_nop 0
	v_add_f32_e32 v37, v37, v38
	v_add_f32_e32 v37, v37, v39
	v_pk_mul_f32 v[38:39], v[4:5], v[40:41]
	s_nop 0
	v_add_f32_e32 v37, v37, v38
	v_add_f32_e32 v37, v37, v39
	v_min_f32_e32 v38, 0, v37
	v_mul_f32_e64 v37, |v37|, s8
	v_exp_f32_e32 v37, v37
	s_nop 0
	v_add_f32_e32 v37, 1.0, v37
	v_cmp_gt_f32_e32 vcc, s5, v37
	s_nop 1
	v_cndmask_b32_e64 v39, 0, 32, vcc
	v_ldexp_f32 v37, v37, v39
	v_log_f32_e32 v37, v37
	s_nop 0
	v_mul_f32_e32 v39, 0x3f317217, v37
	v_fma_f32 v39, v37, s51, -v39
	v_fmac_f32_e32 v39, 0x3377d1cf, v37
	v_fmac_f32_e32 v39, 0x3f317217, v37
	v_cmp_lt_f32_e64 s[12:13], |v37|, s53
	s_nop 1
	v_cndmask_b32_e64 v37, v37, v39, s[12:13]
	v_cndmask_b32_e32 v39, 0, v44, vcc
	v_sub_f32_e32 v37, v37, v39
	v_sub_f32_e32 v37, v38, v37
	ds_read_b128 v[38:41], v25 offset:54080
	v_fmamk_f32 v37, v37, 0x3d800000, v36
	s_waitcnt lgkmcnt(0)
	v_fma_f32 v42, v18, v38, v0
	v_fmac_f32_e32 v42, v19, v39
	v_fmac_f32_e32 v42, v20, v40
	v_fmac_f32_e32 v42, v21, v41
	ds_read_b128 v[38:41], v25 offset:54096
	s_waitcnt lgkmcnt(0)
	v_fmac_f32_e32 v42, v12, v38
	v_fmac_f32_e32 v42, v13, v39
	v_fmac_f32_e32 v42, v14, v40
	v_fmac_f32_e32 v42, v15, v41
	ds_read_b128 v[38:41], v25 offset:54112
	s_waitcnt lgkmcnt(0)
	v_fmac_f32_e32 v42, v8, v38
	v_fmac_f32_e32 v42, v9, v39
	v_fmac_f32_e32 v42, v23, v40
	v_fmac_f32_e32 v42, v24, v41
	ds_read_b128 v[38:41], v25 offset:54128
	s_waitcnt lgkmcnt(0)
	v_pk_mul_f32 v[38:39], v[2:3], v[38:39]
	s_nop 0
	v_add_f32_e32 v38, v42, v38
	v_add_f32_e32 v42, v38, v39
	v_pk_mul_f32 v[38:39], v[4:5], v[40:41]
	s_nop 0
	v_add_f32_e32 v38, v42, v38
	v_add_f32_e32 v38, v38, v39
	v_min_f32_e32 v39, 0, v38
	v_mul_f32_e64 v38, |v38|, s8
	v_exp_f32_e32 v38, v38
	s_nop 0
	v_add_f32_e32 v38, 1.0, v38
	v_cmp_gt_f32_e32 vcc, s5, v38
	s_nop 1
	v_cndmask_b32_e64 v40, 0, 32, vcc
	v_ldexp_f32 v38, v38, v40
	v_log_f32_e32 v38, v38
	s_nop 0
	v_mul_f32_e32 v40, 0x3f317217, v38
	v_fma_f32 v40, v38, s51, -v40
	v_fmac_f32_e32 v40, 0x3377d1cf, v38
	v_fmac_f32_e32 v40, 0x3f317217, v38
	v_cmp_lt_f32_e64 s[12:13], |v38|, s53
	s_nop 1
	v_cndmask_b32_e64 v38, v38, v40, s[12:13]
	v_cndmask_b32_e32 v40, 0, v44, vcc
	v_sub_f32_e32 v38, v38, v40
	ds_read_b128 v[40:43], v25 offset:54144
	v_sub_f32_e32 v38, v39, v38
	v_fmamk_f32 v38, v38, 0x3d800000, v37
	s_waitcnt lgkmcnt(0)
	v_fma_f32 v39, v18, v40, v0
	v_fmac_f32_e32 v39, v19, v41
	v_fmac_f32_e32 v39, v20, v42
	v_fmac_f32_e32 v39, v21, v43
	ds_read_b128 v[40:43], v25 offset:54160
	s_waitcnt lgkmcnt(0)
	v_fmac_f32_e32 v39, v12, v40
	v_fmac_f32_e32 v39, v13, v41
	v_fmac_f32_e32 v39, v14, v42
	v_fmac_f32_e32 v39, v15, v43
	ds_read_b128 v[40:43], v25 offset:54176
	s_waitcnt lgkmcnt(0)
	v_fmac_f32_e32 v39, v8, v40
	v_fmac_f32_e32 v39, v9, v41
	v_fmac_f32_e32 v39, v23, v42
	v_fmac_f32_e32 v39, v24, v43
	ds_read_b128 v[40:43], v25 offset:54192
	s_waitcnt lgkmcnt(0)
	v_pk_mul_f32 v[40:41], v[2:3], v[40:41]
	s_nop 0
	v_add_f32_e32 v39, v39, v40
	v_add_f32_e32 v39, v39, v41
	v_pk_mul_f32 v[40:41], v[4:5], v[42:43]
	s_nop 0
	v_add_f32_e32 v39, v39, v40
	v_add_f32_e32 v39, v39, v41
	v_min_f32_e32 v40, 0, v39
	v_mul_f32_e64 v39, |v39|, s8
	v_exp_f32_e32 v39, v39
	s_nop 0
	v_add_f32_e32 v39, 1.0, v39
	v_cmp_gt_f32_e32 vcc, s5, v39
	s_nop 1
	v_cndmask_b32_e64 v41, 0, 32, vcc
	v_ldexp_f32 v39, v39, v41
	v_log_f32_e32 v39, v39
	s_nop 0
	v_mul_f32_e32 v41, 0x3f317217, v39
	v_fma_f32 v41, v39, s51, -v41
	v_fmac_f32_e32 v41, 0x3377d1cf, v39
	v_fmac_f32_e32 v41, 0x3f317217, v39
	v_cmp_lt_f32_e64 s[12:13], |v39|, s53
	s_nop 1
	v_cndmask_b32_e64 v39, v39, v41, s[12:13]
	v_cndmask_b32_e32 v41, 0, v44, vcc
	v_sub_f32_e32 v39, v39, v41
	v_sub_f32_e32 v39, v40, v39
	ds_read_b128 v[40:43], v25 offset:54208
	v_fmamk_f32 v39, v39, 0x3d800000, v38
	s_waitcnt lgkmcnt(0)
	v_fmac_f32_e32 v0, v18, v40
	v_fmac_f32_e32 v0, v19, v41
	v_fmac_f32_e32 v0, v20, v42
	v_fmac_f32_e32 v0, v21, v43
	ds_read_b128 v[18:21], v25 offset:54224
	s_waitcnt lgkmcnt(0)
	v_fmac_f32_e32 v0, v12, v18
	v_fmac_f32_e32 v0, v13, v19
	v_fmac_f32_e32 v0, v14, v20
	v_fmac_f32_e32 v0, v15, v21
	ds_read_b128 v[12:15], v25 offset:54240
	s_waitcnt lgkmcnt(0)
	v_fmac_f32_e32 v0, v8, v12
	v_fmac_f32_e32 v0, v9, v13
	v_fmac_f32_e32 v0, v23, v14
	v_fmac_f32_e32 v0, v24, v15
	ds_read_b128 v[12:15], v25 offset:54256
	s_waitcnt lgkmcnt(0)
	v_pk_mul_f32 v[2:3], v[2:3], v[12:13]
	s_nop 0
	v_add_f32_e32 v0, v0, v2
	v_add_f32_e32 v0, v0, v3
	v_pk_mul_f32 v[2:3], v[4:5], v[14:15]
	s_nop 0
	v_add_f32_e32 v0, v0, v2
	v_add_f32_e32 v0, v0, v3
	v_min_f32_e32 v2, 0, v0
	v_mul_f32_e64 v0, |v0|, s8
	v_exp_f32_e32 v0, v0
	s_nop 0
	v_add_f32_e32 v0, 1.0, v0
	v_cmp_gt_f32_e32 vcc, s5, v0
	s_nop 1
	v_cndmask_b32_e64 v3, 0, 32, vcc
	v_ldexp_f32 v0, v0, v3
	v_log_f32_e32 v0, v0
	s_nop 0
	v_mul_f32_e32 v3, 0x3f317217, v0
	v_fma_f32 v3, v0, s51, -v3
	v_fmac_f32_e32 v3, 0x3377d1cf, v0
	v_fmac_f32_e32 v3, 0x3f317217, v0
	v_cmp_lt_f32_e64 s[12:13], |v0|, s53
	s_nop 1
	v_cndmask_b32_e64 v0, v0, v3, s[12:13]
	v_cndmask_b32_e32 v3, 0, v44, vcc
	v_sub_f32_e32 v0, v0, v3
	v_sub_f32_e32 v0, v2, v0
	v_fmamk_f32 v9, v0, 0x3d800000, v39
	v_add_u32_e32 v0, 0, v7
	ds_write_b32 v6, v9 offset:51200
	s_waitcnt lgkmcnt(0)
	s_barrier
	ds_read2st64_b32 v[2:3], v0 offset0:200 offset1:202
	v_cmp_lt_i32_e32 vcc, 0, v17
	s_waitcnt lgkmcnt(0)
	v_add_f32_e32 v2, 0, v2
	v_cndmask_b32_e32 v4, 0, v2, vcc
	v_add_f32_e32 v5, v2, v3
	v_cmp_lt_i32_e32 vcc, 1, v17
	v_add_f32_e32 v2, v3, v4
	s_nop 0
	v_cndmask_b32_e32 v4, v4, v2, vcc
	ds_read2st64_b32 v[2:3], v0 offset0:204 offset1:206
	v_cmp_lt_i32_e32 vcc, 2, v17
	s_waitcnt lgkmcnt(0)
	v_add_f32_e32 v0, v5, v2
	v_add_f32_e32 v2, v2, v4
	v_cndmask_b32_e32 v2, v4, v2, vcc
	v_add_f32_e32 v18, v0, v3
	v_cmp_lt_i32_e32 vcc, 3, v17
	v_add_f32_e32 v0, v3, v2
	s_nop 0
	v_cndmask_b32_e32 v0, v2, v0, vcc
	v_lshlrev_b32_e32 v2, 4, v17
	v_ashrrev_i32_e32 v3, 31, v2
	v_lshl_add_u64 v[2:3], s[6:7], 0, v[2:3]
	v_lshlrev_b64 v[2:3], 13, v[2:3]
	v_lshl_add_u64 v[2:3], s[18:19], 0, v[2:3]
	v_sub_f32_e32 v15, v18, v0
	v_lshl_add_u64 v[2:3], v[2:3], 0, s[86:87]
	v_lshlrev_b32_e32 v0, 1, v11
	v_lshl_add_u64 v[12:13], v[2:3], 0, v[0:1]
	s_mov_b64 s[100:101], 0x2000
	global_load_ushort v108, v[12:13], off offset:2688
	v_lshl_add_u64 v[124:125], v[12:13], 0, s[100:101]
	global_load_ushort v109, v[124:125], off offset:2688
	v_lshl_add_u64 v[124:125], v[124:125], 0, s[100:101]
	global_load_ushort v110, v[124:125], off offset:2688
	v_lshl_add_u64 v[124:125], v[124:125], 0, s[100:101]
	global_load_ushort v111, v[124:125], off offset:2688
	v_lshl_add_u64 v[124:125], v[124:125], 0, s[100:101]
	global_load_ushort v112, v[124:125], off offset:2688
	v_lshl_add_u64 v[124:125], v[124:125], 0, s[100:101]
	global_load_ushort v113, v[124:125], off offset:2688
	v_lshl_add_u64 v[124:125], v[124:125], 0, s[100:101]
	global_load_ushort v114, v[124:125], off offset:2688
	v_lshl_add_u64 v[124:125], v[124:125], 0, s[100:101]
	global_load_ushort v115, v[124:125], off offset:2688
	v_lshl_add_u64 v[124:125], v[124:125], 0, s[100:101]
	global_load_ushort v116, v[124:125], off offset:2688
	v_lshl_add_u64 v[124:125], v[124:125], 0, s[100:101]
	global_load_ushort v117, v[124:125], off offset:2688
	v_lshl_add_u64 v[124:125], v[124:125], 0, s[100:101]
	global_load_ushort v118, v[124:125], off offset:2688
	v_lshl_add_u64 v[124:125], v[124:125], 0, s[100:101]
	global_load_ushort v119, v[124:125], off offset:2688
	v_lshl_add_u64 v[124:125], v[124:125], 0, s[100:101]
	global_load_ushort v120, v[124:125], off offset:2688
	v_lshl_add_u64 v[124:125], v[124:125], 0, s[100:101]
	global_load_ushort v121, v[124:125], off offset:2688
	v_lshl_add_u64 v[124:125], v[124:125], 0, s[100:101]
	global_load_ushort v122, v[124:125], off offset:2688
	v_lshl_add_u64 v[124:125], v[124:125], 0, s[100:101]
	global_load_ushort v123, v[124:125], off offset:2688
	v_sub_f32_e32 v0, v15, v22
	v_mul_f32_e32 v0, 0x3fb8aa3b, v0
	v_exp_f32_e32 v2, v0
	v_sub_f32_e32 v0, v15, v26
	v_add_co_u32_e32 v4, vcc, s37, v12
	v_mul_f32_e32 v0, 0x3fb8aa3b, v0
	s_nop 0
	v_addc_co_u32_e32 v5, vcc, 0, v13, vcc
	v_exp_f32_e32 v3, v0
	s_waitcnt vmcnt(0)
	v_mov_b32_e32 v0, v109
	s_nop 0
	v_mov_b32_e32 v4, v108
	v_add_co_u32_e32 v6, vcc, s79, v12
	s_waitcnt vmcnt(0)
	v_lshlrev_b32_e32 v5, 16, v0
	v_sub_f32_e32 v0, v15, v27
	s_waitcnt vmcnt(0)
	v_lshlrev_b32_e32 v4, 16, v4
	v_mul_f32_e32 v0, 0x3fb8aa3b, v0
	v_pk_mul_f32 v[2:3], v[2:3], v[4:5]
	v_exp_f32_e32 v4, v0
	v_sub_f32_e32 v0, v15, v28
	v_mul_f32_e32 v0, 0x3fb8aa3b, v0
	v_addc_co_u32_e32 v7, vcc, 0, v13, vcc
	v_exp_f32_e32 v5, v0
	v_mov_b32_e32 v0, v110
	v_add_co_u32_e32 v6, vcc, s57, v12
	v_cvt_pk_bf16_f32 v2, v2, v3
	s_nop 0
	v_addc_co_u32_e32 v7, vcc, 0, v13, vcc
	v_mov_b32_e32 v3, v111
	s_waitcnt vmcnt(1)
	v_lshlrev_b32_e32 v6, 16, v0
	v_sub_f32_e32 v0, v15, v29
	v_mul_f32_e32 v0, 0x3fb8aa3b, v0
	s_waitcnt vmcnt(0)
	v_lshlrev_b32_e32 v7, 16, v3
	v_pk_mul_f32 v[4:5], v[4:5], v[6:7]
	v_add_co_u32_e32 v6, vcc, s0, v12
	v_cvt_pk_bf16_f32 v3, v4, v5
	v_exp_f32_e32 v4, v0
	v_sub_f32_e32 v0, v15, v30
	v_mul_f32_e32 v0, 0x3fb8aa3b, v0
	v_addc_co_u32_e32 v7, vcc, 0, v13, vcc
	s_mov_b32 s0, 0xa000
	v_exp_f32_e32 v5, v0
	v_mov_b32_e32 v0, v112
	v_add_co_u32_e32 v6, vcc, s0, v12
	s_mov_b32 s0, 0xe000
	s_nop 0
	v_addc_co_u32_e32 v7, vcc, 0, v13, vcc
	v_mov_b32_e32 v6, v113
	v_add_co_u32_e32 v20, vcc, s48, v12
	s_waitcnt vmcnt(0)
	v_lshlrev_b32_e32 v7, 16, v6
	v_lshlrev_b32_e32 v6, 16, v0
	v_sub_f32_e32 v0, v15, v31
	v_mul_f32_e32 v0, 0x3fb8aa3b, v0
	v_pk_mul_f32 v[4:5], v[4:5], v[6:7]
	v_exp_f32_e32 v6, v0
	v_sub_f32_e32 v0, v15, v32
	v_mul_f32_e32 v0, 0x3fb8aa3b, v0
	v_addc_co_u32_e32 v21, vcc, 0, v13, vcc
	v_exp_f32_e32 v7, v0
	v_mov_b32_e32 v0, v114
	v_add_co_u32_e32 v20, vcc, s0, v12
	v_cvt_pk_bf16_f32 v4, v4, v5
	s_nop 0
	v_addc_co_u32_e32 v21, vcc, 0, v13, vcc
	v_mov_b32_e32 v5, v115
	s_mov_b32 s0, 0x10000
	s_waitcnt vmcnt(1)
	v_lshlrev_b32_e32 v20, 16, v0
	v_sub_f32_e32 v0, v15, v33
	v_mul_f32_e32 v0, 0x3fb8aa3b, v0
	s_waitcnt vmcnt(0)
	v_lshlrev_b32_e32 v21, 16, v5
	v_pk_mul_f32 v[6:7], v[6:7], v[20:21]
	v_add_co_u32_e32 v20, vcc, s0, v12
	v_cvt_pk_bf16_f32 v5, v6, v7
	v_exp_f32_e32 v6, v0
	v_sub_f32_e32 v0, v15, v34
	v_mul_f32_e32 v0, 0x3fb8aa3b, v0
	v_addc_co_u32_e32 v21, vcc, 0, v13, vcc
	v_exp_f32_e32 v7, v0
	v_mov_b32_e32 v0, v116
	v_add_co_u32_e32 v20, vcc, s58, v12
	s_mov_b32 s0, 0x14000
	s_nop 0
	v_addc_co_u32_e32 v21, vcc, 0, v13, vcc
	v_mov_b32_e32 v8, v117
	v_add_co_u32_e32 v22, vcc, s0, v12
	s_mov_b32 s0, 0x1a000
	s_nop 0
	v_addc_co_u32_e32 v23, vcc, 0, v13, vcc
	s_waitcnt vmcnt(1)
	v_lshlrev_b32_e32 v20, 16, v0
	v_sub_f32_e32 v0, v15, v35
	v_mul_f32_e32 v0, 0x3fb8aa3b, v0
	s_waitcnt vmcnt(0)
	v_lshlrev_b32_e32 v21, 16, v8
	v_pk_mul_f32 v[6:7], v[6:7], v[20:21]
	v_exp_f32_e32 v20, v0
	v_sub_f32_e32 v0, v15, v36
	v_mul_f32_e32 v0, 0x3fb8aa3b, v0
	v_exp_f32_e32 v21, v0
	v_mov_b32_e32 v0, v118
	v_add_co_u32_e32 v22, vcc, s36, v12
	v_cvt_pk_bf16_f32 v6, v6, v7
	s_nop 0
	v_addc_co_u32_e32 v23, vcc, 0, v13, vcc
	v_mov_b32_e32 v7, v119
	s_waitcnt vmcnt(1)
	v_lshlrev_b32_e32 v22, 16, v0
	v_sub_f32_e32 v0, v15, v37
	v_mul_f32_e32 v0, 0x3fb8aa3b, v0
	s_waitcnt vmcnt(0)
	v_lshlrev_b32_e32 v23, 16, v7
	v_pk_mul_f32 v[20:21], v[20:21], v[22:23]
	v_add_co_u32_e32 v22, vcc, s52, v12
	v_cvt_pk_bf16_f32 v7, v20, v21
	v_exp_f32_e32 v20, v0
	v_sub_f32_e32 v0, v15, v38
	v_mul_f32_e32 v0, 0x3fb8aa3b, v0
	v_addc_co_u32_e32 v23, vcc, 0, v13, vcc
	v_exp_f32_e32 v21, v0
	v_mov_b32_e32 v0, v120
	v_add_co_u32_e32 v22, vcc, s0, v12
	s_mov_b32 s0, 0x1c000
	s_nop 0
	v_addc_co_u32_e32 v23, vcc, 0, v13, vcc
	v_mov_b32_e32 v8, v121
	s_waitcnt vmcnt(1)
	v_lshlrev_b32_e32 v22, 16, v0
	v_sub_f32_e32 v0, v15, v39
	v_mul_f32_e32 v0, 0x3fb8aa3b, v0
	v_exp_f32_e32 v14, v0
	v_sub_f32_e32 v0, v15, v9
	v_mul_f32_e32 v0, 0x3fb8aa3b, v0
	s_waitcnt vmcnt(0)
	v_lshlrev_b32_e32 v23, 16, v8
	v_pk_mul_f32 v[20:21], v[20:21], v[22:23]
	v_exp_f32_e32 v15, v0
	v_cvt_pk_bf16_f32 v8, v20, v21
	v_add_co_u32_e32 v20, vcc, s0, v12
	s_movk_i32 s0, 0x80
	s_nop 0
	v_addc_co_u32_e32 v21, vcc, 0, v13, vcc
	v_add_co_u32_e32 v12, vcc, s59, v12
	v_mov_b32_e32 v0, v122
	s_nop 0
	v_addc_co_u32_e32 v13, vcc, 0, v13, vcc
	v_mov_b32_e32 v9, v123
	v_cmp_gt_u32_e32 vcc, s0, v10
	s_waitcnt vmcnt(1)
	v_lshlrev_b32_e32 v12, 16, v0
	v_mul_u32_u24_e32 v0, 0x90, v11
	v_lshlrev_b32_e32 v11, 5, v17
	s_waitcnt vmcnt(0)
	v_lshlrev_b32_e32 v13, 16, v9
	v_pk_mul_f32 v[12:13], v[14:15], v[12:13]
	v_add3_u32 v0, 0, v0, v11
	v_cvt_pk_bf16_f32 v9, v12, v13
	ds_write_b128 v0, v[2:5] offset:32768
	ds_write_b128 v0, v[6:9] offset:32784
	s_and_saveexec_b64 s[6:7], vcc
	s_cbranch_execz .LBB0_388
	v_mul_f32_e32 v0, 0x3fb8aa3b, v18
	v_exp_f32_e32 v0, v0
	v_mov_b32_e32 v11, v1
	v_lshl_add_u64 v[2:3], v[10:11], 2, s[26:27]
	global_store_dword v[2:3], v0, off
	s_branch .LBB0_388
